# nt hint also on the residual-update epilogue loads (own tile, read once) and the chunk-scan state loads
# speedup vs baseline: 1.0395x; 1.0068x over previous
.LBB0_184:
	v_and_b32_e32 v133, 64, v216
	v_xor_b32_e32 v132, 16, v216
	v_add_u32_e32 v133, 64, v133
	v_cmp_lt_i32_e32 vcc, v132, v133
	s_lshl_b32 s17, s17, 8
	v_lshl_or_b32 v170, s16, 8, v192
	v_cndmask_b32_e32 v132, v216, v132, vcc
	v_add_u32_e32 v172, s17, v3
	v_ashrrev_i32_e32 v171, 31, v170
	v_lshlrev_b32_e32 v195, 2, v132
	v_xor_b32_e32 v132, 32, v216
	v_cmp_lt_i32_e32 vcc, v132, v133
	v_lshlrev_b64 v[182:183], 1, v[170:171]
	v_ashrrev_i32_e32 v173, 31, v172
	v_cndmask_b32_e32 v132, v216, v132, vcc
	v_lshl_add_u64 v[174:175], s[42:43], 0, v[182:183]
	v_lshlrev_b64 v[184:185], 11, v[172:173]
	v_lshlrev_b32_e32 v180, 2, v132
	v_lshl_add_u64 v[132:133], v[174:175], 0, v[184:185]
	global_load_dwordx4 v[196:199], v[132:133], off nt
	global_load_dwordx4 v[156:159], v[132:133], off offset:256 nt
	v_or_b32_e32 v132, 16, v172
	v_ashrrev_i32_e32 v133, 31, v132
	v_lshlrev_b64 v[190:191], 11, v[132:133]
	v_lshl_add_u64 v[132:133], v[174:175], 0, v[190:191]
	global_load_dwordx4 v[152:155], v[132:133], off nt
	global_load_dwordx4 v[148:151], v[132:133], off offset:256 nt
	v_or_b32_e32 v132, 32, v172
	v_ashrrev_i32_e32 v133, 31, v132
	v_lshlrev_b64 v[178:179], 11, v[132:133]
	v_lshl_add_u64 v[132:133], v[174:175], 0, v[178:179]
	global_load_dwordx4 v[144:147], v[132:133], off nt
	global_load_dwordx4 v[140:143], v[132:133], off offset:256 nt
	v_or_b32_e32 v132, 48, v172
	v_ashrrev_i32_e32 v133, 31, v132
	v_lshlrev_b64 v[176:177], 11, v[132:133]
	v_lshl_add_u64 v[132:133], v[174:175], 0, v[176:177]
	global_load_dwordx4 v[136:139], v[132:133], off nt
	s_nop 0
	global_load_dwordx4 v[132:135], v[132:133], off offset:256 nt
	s_waitcnt vmcnt(0)
	v_lshlrev_b32_e32 v200, 16, v196
	v_and_b32_e32 v201, 0xffff0000, v196
	v_lshlrev_b32_e32 v196, 16, v197
	v_and_b32_e32 v197, 0xffff0000, v197
	v_lshlrev_b32_e32 v202, 16, v198
	v_and_b32_e32 v203, 0xffff0000, v198
	v_lshlrev_b32_e32 v198, 16, v199
	v_and_b32_e32 v199, 0xffff0000, v199
	v_pk_add_f32 v[130:131], v[130:131], v[196:197]
	v_pk_add_f32 v[128:129], v[128:129], v[200:201]
	v_pk_add_f32 v[196:197], v[126:127], v[198:199]
	v_mul_f32_e32 v126, v129, v129
	v_mul_f32_e32 v127, v131, v131
	v_pk_add_f32 v[124:125], v[124:125], v[202:203]
	v_fmac_f32_e32 v126, v128, v128
	v_fmac_f32_e32 v127, v130, v130
	v_add_f32_e32 v126, v126, v127
	v_mul_f32_e32 v127, v125, v125
	v_fmac_f32_e32 v127, v124, v124
	v_add_f32_e32 v126, v127, v126
	v_mul_f32_e32 v127, v197, v197
	v_fmac_f32_e32 v127, v196, v196
	v_add_f32_e32 v198, v127, v126
	v_cvt_pk_bf16_f32 v126, v128, v129
	v_cvt_pk_bf16_f32 v128, v124, v125
	v_lshl_add_u64 v[124:125], s[42:43], 0, v[184:185]
	v_cvt_pk_bf16_f32 v127, v130, v131
	v_cvt_pk_bf16_f32 v129, v196, v197
	v_lshl_add_u64 v[124:125], v[124:125], 0, v[182:183]
	global_store_dwordx4 v[124:125], v[126:129], off
	v_lshlrev_b32_e32 v130, 16, v158
	v_and_b32_e32 v131, 0xffff0000, v158
	v_lshlrev_b32_e32 v126, 16, v156
	v_and_b32_e32 v127, 0xffff0000, v156
	v_lshlrev_b32_e32 v128, 16, v157
	v_and_b32_e32 v129, 0xffff0000, v157
	v_lshlrev_b32_e32 v156, 16, v159
	v_and_b32_e32 v157, 0xffff0000, v159
	v_pk_add_f32 v[122:123], v[122:123], v[128:129]
	v_pk_add_f32 v[120:121], v[120:121], v[126:127]
	v_pk_add_f32 v[126:127], v[118:119], v[156:157]
	v_pk_add_f32 v[118:119], v[116:117], v[130:131]
	v_mul_f32_e32 v116, v121, v121
	v_mul_f32_e32 v117, v123, v123
	v_fmac_f32_e32 v116, v120, v120
	v_fmac_f32_e32 v117, v122, v122
	v_add_f32_e32 v116, v116, v117
	v_mul_f32_e32 v117, v119, v119
	v_fmac_f32_e32 v117, v118, v118
	v_add_f32_e32 v116, v117, v116
	v_mul_f32_e32 v117, v127, v127
	v_fmac_f32_e32 v117, v126, v126
	v_add_f32_e32 v116, v117, v116
	v_add_f32_e32 v128, v198, v116
	v_cvt_pk_bf16_f32 v116, v120, v121
	v_cvt_pk_bf16_f32 v117, v122, v123
	v_cvt_pk_bf16_f32 v118, v118, v119
	v_cvt_pk_bf16_f32 v119, v126, v127
	global_store_dwordx4 v[124:125], v[116:119], off offset:256
	ds_bpermute_b32 v116, v195, v128
	s_waitcnt lgkmcnt(0)
	v_add_f32_e32 v116, v128, v116
	ds_bpermute_b32 v117, v180, v116
	s_and_saveexec_b64 s[10:11], s[6:7]
	s_cbranch_execz .LBB0_186
	s_waitcnt lgkmcnt(0)
	v_add_f32_e32 v116, v116, v117
	ds_write_b32 v193, v116

.LBB0_192:
	s_or_b64 exec, exec, s[10:11]
	s_waitcnt lgkmcnt(0)
	v_lshlrev_b64 v[68:69], 11, v[172:173]
	s_mov_b64 s[10:11], 0x40000
	v_lshl_add_u64 v[106:107], v[68:69], 0, s[10:11]
	v_lshl_add_u64 v[70:71], v[174:175], 0, v[106:107]
	global_load_dwordx4 v[98:101], v[70:71], off nt
	global_load_dwordx4 v[102:105], v[70:71], off offset:256 nt
	s_mov_b64 s[10:11], 0x48000
	v_lshl_add_u64 v[96:97], v[68:69], 0, s[10:11]
	s_mov_b64 s[10:11], 0x50000
	v_lshl_add_u64 v[94:95], v[68:69], 0, s[10:11]
	s_mov_b64 s[10:11], 0x58000
	v_lshl_add_u64 v[70:71], v[174:175], 0, v[96:97]
	v_lshl_add_u64 v[92:93], v[68:69], 0, s[10:11]
	global_load_dwordx4 v[88:91], v[70:71], off nt
	global_load_dwordx4 v[84:87], v[70:71], off offset:256 nt
	v_lshl_add_u64 v[70:71], v[174:175], 0, v[94:95]
	v_lshl_add_u64 v[68:69], v[174:175], 0, v[92:93]
	global_load_dwordx4 v[80:83], v[70:71], off nt
	global_load_dwordx4 v[76:79], v[70:71], off offset:256 nt
	global_load_dwordx4 v[72:75], v[68:69], off nt
	s_nop 0
	global_load_dwordx4 v[68:71], v[68:69], off offset:256 nt
	s_waitcnt vmcnt(7)
	v_lshlrev_b32_e32 v108, 16, v98
	v_and_b32_e32 v109, 0xffff0000, v98
	v_lshlrev_b32_e32 v98, 16, v99
	v_and_b32_e32 v99, 0xffff0000, v99
	v_lshlrev_b32_e32 v110, 16, v100
	v_and_b32_e32 v111, 0xffff0000, v100
	v_lshlrev_b32_e32 v100, 16, v101
	v_and_b32_e32 v101, 0xffff0000, v101
	v_pk_add_f32 v[66:67], v[66:67], v[98:99]
	v_pk_add_f32 v[64:65], v[64:65], v[108:109]
	v_pk_add_f32 v[98:99], v[62:63], v[100:101]
	v_mul_f32_e32 v62, v65, v65
	v_mul_f32_e32 v63, v67, v67
	v_pk_add_f32 v[60:61], v[60:61], v[110:111]
	v_fmac_f32_e32 v62, v64, v64
	v_fmac_f32_e32 v63, v66, v66
	v_add_f32_e32 v62, v62, v63
	v_mul_f32_e32 v63, v61, v61
	v_fmac_f32_e32 v63, v60, v60
	v_add_f32_e32 v62, v63, v62
	v_mul_f32_e32 v63, v99, v99
	v_fmac_f32_e32 v63, v98, v98
	v_add_f32_e32 v100, v63, v62
	v_cvt_pk_bf16_f32 v62, v64, v65
	v_cvt_pk_bf16_f32 v64, v60, v61
	v_lshl_add_u64 v[60:61], s[42:43], 0, v[106:107]
	v_cvt_pk_bf16_f32 v63, v66, v67
	v_cvt_pk_bf16_f32 v65, v98, v99
	v_lshl_add_u64 v[60:61], v[170:171], 1, v[60:61]
	global_store_dwordx4 v[60:61], v[62:65], off
	s_waitcnt vmcnt(7)
	v_lshlrev_b32_e32 v66, 16, v104
	v_and_b32_e32 v67, 0xffff0000, v104
	v_lshlrev_b32_e32 v62, 16, v102
	v_and_b32_e32 v63, 0xffff0000, v102
	v_lshlrev_b32_e32 v64, 16, v103
	v_and_b32_e32 v65, 0xffff0000, v103
	v_lshlrev_b32_e32 v98, 16, v105
	v_and_b32_e32 v99, 0xffff0000, v105
	v_pk_add_f32 v[58:59], v[58:59], v[64:65]
	v_pk_add_f32 v[56:57], v[56:57], v[62:63]
	v_pk_add_f32 v[62:63], v[54:55], v[98:99]
	v_pk_add_f32 v[54:55], v[52:53], v[66:67]
	v_mul_f32_e32 v52, v57, v57
	v_mul_f32_e32 v53, v59, v59
	v_fmac_f32_e32 v52, v56, v56
	v_fmac_f32_e32 v53, v58, v58
	v_add_f32_e32 v52, v52, v53
	v_mul_f32_e32 v53, v55, v55
	v_fmac_f32_e32 v53, v54, v54
	v_add_f32_e32 v52, v53, v52
	v_mul_f32_e32 v53, v63, v63
	v_fmac_f32_e32 v53, v62, v62
	v_add_f32_e32 v52, v53, v52
	v_add_f32_e32 v64, v100, v52
	v_cvt_pk_bf16_f32 v52, v56, v57
	v_cvt_pk_bf16_f32 v53, v58, v59
	v_cvt_pk_bf16_f32 v54, v54, v55
	v_cvt_pk_bf16_f32 v55, v62, v63
	global_store_dwordx4 v[60:61], v[52:55], off offset:256
	ds_bpermute_b32 v52, v195, v64
	s_waitcnt lgkmcnt(0)
	v_add_f32_e32 v52, v64, v52
	ds_bpermute_b32 v53, v180, v52
	s_and_saveexec_b64 s[10:11], s[6:7]
	s_cbranch_execz .LBB0_194
	s_waitcnt lgkmcnt(0)
	v_add_f32_e32 v52, v52, v53
	ds_write_b32 v193, v52 offset:2048

.LBB0_337:
	v_and_b32_e32 v133, 64, v216
	v_xor_b32_e32 v132, 16, v216
	v_add_u32_e32 v133, 64, v133
	v_cmp_lt_i32_e32 vcc, v132, v133
	s_lshl_b32 s15, s15, 8
	v_lshl_or_b32 v170, s14, 8, v192
	v_cndmask_b32_e32 v132, v216, v132, vcc
	v_add_u32_e32 v172, s15, v3
	v_ashrrev_i32_e32 v171, 31, v170
	v_lshlrev_b32_e32 v195, 2, v132
	v_xor_b32_e32 v132, 32, v216
	v_cmp_lt_i32_e32 vcc, v132, v133
	v_lshlrev_b64 v[182:183], 1, v[170:171]
	v_ashrrev_i32_e32 v173, 31, v172
	v_cndmask_b32_e32 v132, v216, v132, vcc
	v_lshl_add_u64 v[174:175], s[42:43], 0, v[182:183]
	v_lshlrev_b64 v[184:185], 11, v[172:173]
	v_lshlrev_b32_e32 v180, 2, v132
	v_lshl_add_u64 v[132:133], v[174:175], 0, v[184:185]
	global_load_dwordx4 v[196:199], v[132:133], off nt
	global_load_dwordx4 v[156:159], v[132:133], off offset:256 nt
	v_or_b32_e32 v132, 16, v172
	v_ashrrev_i32_e32 v133, 31, v132
	v_lshlrev_b64 v[190:191], 11, v[132:133]
	v_lshl_add_u64 v[132:133], v[174:175], 0, v[190:191]
	global_load_dwordx4 v[152:155], v[132:133], off nt
	global_load_dwordx4 v[148:151], v[132:133], off offset:256 nt
	v_or_b32_e32 v132, 32, v172
	v_ashrrev_i32_e32 v133, 31, v132
	v_lshlrev_b64 v[178:179], 11, v[132:133]
	v_lshl_add_u64 v[132:133], v[174:175], 0, v[178:179]
	global_load_dwordx4 v[144:147], v[132:133], off nt
	global_load_dwordx4 v[140:143], v[132:133], off offset:256 nt
	v_or_b32_e32 v132, 48, v172
	v_ashrrev_i32_e32 v133, 31, v132
	v_lshlrev_b64 v[176:177], 11, v[132:133]
	v_lshl_add_u64 v[132:133], v[174:175], 0, v[176:177]
	global_load_dwordx4 v[136:139], v[132:133], off nt
	s_nop 0
	global_load_dwordx4 v[132:135], v[132:133], off offset:256 nt
	s_waitcnt vmcnt(0)
	v_lshlrev_b32_e32 v200, 16, v196
	v_and_b32_e32 v201, 0xffff0000, v196
	v_lshlrev_b32_e32 v196, 16, v197
	v_and_b32_e32 v197, 0xffff0000, v197
	v_lshlrev_b32_e32 v202, 16, v198
	v_and_b32_e32 v203, 0xffff0000, v198
	v_lshlrev_b32_e32 v198, 16, v199
	v_and_b32_e32 v199, 0xffff0000, v199
	v_pk_add_f32 v[130:131], v[130:131], v[196:197]
	v_pk_add_f32 v[128:129], v[128:129], v[200:201]
	v_pk_add_f32 v[196:197], v[126:127], v[198:199]
	v_mul_f32_e32 v126, v129, v129
	v_mul_f32_e32 v127, v131, v131
	v_pk_add_f32 v[124:125], v[124:125], v[202:203]
	v_fmac_f32_e32 v126, v128, v128
	v_fmac_f32_e32 v127, v130, v130
	v_add_f32_e32 v126, v126, v127
	v_mul_f32_e32 v127, v125, v125
	v_fmac_f32_e32 v127, v124, v124
	v_add_f32_e32 v126, v127, v126
	v_mul_f32_e32 v127, v197, v197
	v_fmac_f32_e32 v127, v196, v196
	v_add_f32_e32 v198, v127, v126
	v_cvt_pk_bf16_f32 v126, v128, v129
	v_cvt_pk_bf16_f32 v128, v124, v125
	v_lshl_add_u64 v[124:125], s[42:43], 0, v[184:185]
	v_cvt_pk_bf16_f32 v127, v130, v131
	v_cvt_pk_bf16_f32 v129, v196, v197
	v_lshl_add_u64 v[124:125], v[124:125], 0, v[182:183]
	global_store_dwordx4 v[124:125], v[126:129], off
	v_lshlrev_b32_e32 v130, 16, v158
	v_and_b32_e32 v131, 0xffff0000, v158
	v_lshlrev_b32_e32 v126, 16, v156
	v_and_b32_e32 v127, 0xffff0000, v156
	v_lshlrev_b32_e32 v128, 16, v157
	v_and_b32_e32 v129, 0xffff0000, v157
	v_lshlrev_b32_e32 v156, 16, v159
	v_and_b32_e32 v157, 0xffff0000, v159
	v_pk_add_f32 v[122:123], v[122:123], v[128:129]
	v_pk_add_f32 v[120:121], v[120:121], v[126:127]
	v_pk_add_f32 v[126:127], v[118:119], v[156:157]
	v_pk_add_f32 v[118:119], v[116:117], v[130:131]
	v_mul_f32_e32 v116, v121, v121
	v_mul_f32_e32 v117, v123, v123
	v_fmac_f32_e32 v116, v120, v120
	v_fmac_f32_e32 v117, v122, v122
	v_add_f32_e32 v116, v116, v117
	v_mul_f32_e32 v117, v119, v119
	v_fmac_f32_e32 v117, v118, v118
	v_add_f32_e32 v116, v117, v116
	v_mul_f32_e32 v117, v127, v127
	v_fmac_f32_e32 v117, v126, v126
	v_add_f32_e32 v116, v117, v116
	v_add_f32_e32 v128, v198, v116
	v_cvt_pk_bf16_f32 v116, v120, v121
	v_cvt_pk_bf16_f32 v117, v122, v123
	v_cvt_pk_bf16_f32 v118, v118, v119
	v_cvt_pk_bf16_f32 v119, v126, v127
	global_store_dwordx4 v[124:125], v[116:119], off offset:256
	ds_bpermute_b32 v116, v195, v128
	s_waitcnt lgkmcnt(0)
	v_add_f32_e32 v116, v128, v116
	ds_bpermute_b32 v117, v180, v116
	s_and_saveexec_b64 s[44:45], s[6:7]
	s_cbranch_execz .LBB0_339
	s_waitcnt lgkmcnt(0)
	v_add_f32_e32 v116, v116, v117
	ds_write_b32 v193, v116

.LBB0_345:
	s_or_b64 exec, exec, s[44:45]
	s_waitcnt lgkmcnt(0)
	v_lshlrev_b64 v[68:69], 11, v[172:173]
	s_mov_b64 s[40:41], 0x40000
	v_lshl_add_u64 v[106:107], v[68:69], 0, s[40:41]
	v_lshl_add_u64 v[70:71], v[174:175], 0, v[106:107]
	global_load_dwordx4 v[98:101], v[70:71], off nt
	global_load_dwordx4 v[102:105], v[70:71], off offset:256 nt
	s_mov_b64 s[40:41], 0x48000
	v_lshl_add_u64 v[96:97], v[68:69], 0, s[40:41]
	s_mov_b64 s[40:41], 0x50000
	v_lshl_add_u64 v[94:95], v[68:69], 0, s[40:41]
	s_mov_b64 s[40:41], 0x58000
	v_lshl_add_u64 v[70:71], v[174:175], 0, v[96:97]
	v_lshl_add_u64 v[92:93], v[68:69], 0, s[40:41]
	global_load_dwordx4 v[88:91], v[70:71], off nt
	global_load_dwordx4 v[84:87], v[70:71], off offset:256 nt
	v_lshl_add_u64 v[70:71], v[174:175], 0, v[94:95]
	v_lshl_add_u64 v[68:69], v[174:175], 0, v[92:93]
	global_load_dwordx4 v[80:83], v[70:71], off nt
	global_load_dwordx4 v[76:79], v[70:71], off offset:256 nt
	global_load_dwordx4 v[72:75], v[68:69], off nt
	s_nop 0
	global_load_dwordx4 v[68:71], v[68:69], off offset:256 nt
	s_waitcnt vmcnt(7)
	v_lshlrev_b32_e32 v108, 16, v98
	v_and_b32_e32 v109, 0xffff0000, v98
	v_lshlrev_b32_e32 v98, 16, v99
	v_and_b32_e32 v99, 0xffff0000, v99
	v_lshlrev_b32_e32 v110, 16, v100
	v_and_b32_e32 v111, 0xffff0000, v100
	v_lshlrev_b32_e32 v100, 16, v101
	v_and_b32_e32 v101, 0xffff0000, v101
	v_pk_add_f32 v[66:67], v[66:67], v[98:99]
	v_pk_add_f32 v[64:65], v[64:65], v[108:109]
	v_pk_add_f32 v[98:99], v[62:63], v[100:101]
	v_mul_f32_e32 v62, v65, v65
	v_mul_f32_e32 v63, v67, v67
	v_pk_add_f32 v[60:61], v[60:61], v[110:111]
	v_fmac_f32_e32 v62, v64, v64
	v_fmac_f32_e32 v63, v66, v66
	v_add_f32_e32 v62, v62, v63
	v_mul_f32_e32 v63, v61, v61
	v_fmac_f32_e32 v63, v60, v60
	v_add_f32_e32 v62, v63, v62
	v_mul_f32_e32 v63, v99, v99
	v_fmac_f32_e32 v63, v98, v98
	v_add_f32_e32 v100, v63, v62
	v_cvt_pk_bf16_f32 v62, v64, v65
	v_cvt_pk_bf16_f32 v64, v60, v61
	v_lshl_add_u64 v[60:61], s[42:43], 0, v[106:107]
	v_cvt_pk_bf16_f32 v63, v66, v67
	v_cvt_pk_bf16_f32 v65, v98, v99
	v_lshl_add_u64 v[60:61], v[170:171], 1, v[60:61]
	global_store_dwordx4 v[60:61], v[62:65], off
	s_waitcnt vmcnt(7)
	v_lshlrev_b32_e32 v66, 16, v104
	v_and_b32_e32 v67, 0xffff0000, v104
	v_lshlrev_b32_e32 v62, 16, v102
	v_and_b32_e32 v63, 0xffff0000, v102
	v_lshlrev_b32_e32 v64, 16, v103
	v_and_b32_e32 v65, 0xffff0000, v103
	v_lshlrev_b32_e32 v98, 16, v105
	v_and_b32_e32 v99, 0xffff0000, v105
	v_pk_add_f32 v[58:59], v[58:59], v[64:65]
	v_pk_add_f32 v[56:57], v[56:57], v[62:63]
	v_pk_add_f32 v[62:63], v[54:55], v[98:99]
	v_pk_add_f32 v[54:55], v[52:53], v[66:67]
	v_mul_f32_e32 v52, v57, v57
	v_mul_f32_e32 v53, v59, v59
	v_fmac_f32_e32 v52, v56, v56
	v_fmac_f32_e32 v53, v58, v58
	v_add_f32_e32 v52, v52, v53
	v_mul_f32_e32 v53, v55, v55
	v_fmac_f32_e32 v53, v54, v54
	v_add_f32_e32 v52, v53, v52
	v_mul_f32_e32 v53, v63, v63
	v_fmac_f32_e32 v53, v62, v62
	v_add_f32_e32 v52, v53, v52
	v_add_f32_e32 v64, v100, v52
	v_cvt_pk_bf16_f32 v52, v56, v57
	v_cvt_pk_bf16_f32 v53, v58, v59
	v_cvt_pk_bf16_f32 v54, v54, v55
	v_cvt_pk_bf16_f32 v55, v62, v63
	global_store_dwordx4 v[60:61], v[52:55], off offset:256
	ds_bpermute_b32 v52, v195, v64
	s_waitcnt lgkmcnt(0)
	v_add_f32_e32 v52, v64, v52
	ds_bpermute_b32 v53, v180, v52
	s_and_saveexec_b64 s[44:45], s[6:7]
	s_cbranch_execz .LBB0_347
	s_waitcnt lgkmcnt(0)
	v_add_f32_e32 v52, v52, v53
	ds_write_b32 v193, v52 offset:2048

.LBB0_366:
	s_and_saveexec_b64 s[10:11], vcc
	s_cbranch_execz .LBB0_365
	s_and_b32 s13, s19, 7
	s_mul_i32 s8, s13, 0x480
	v_add_u32_e32 v0, s8, v186
	s_ashr_i32 s8, s19, 5
	s_ashr_i32 s9, s8, 31
	v_readlane_b32 s44, v251, 4
	s_and_b32 s12, s18, 0xffffffe0
	s_lshl_b64 s[8:9], s[8:9], 23
	v_readlane_b32 s58, v251, 18
	v_readlane_b32 s59, v251, 19
	s_add_u32 s8, s58, s8
	s_addc_u32 s9, s59, s9
	s_and_b32 s14, s18, 0x60
	v_ashrrev_i32_e32 v1, 31, v0
	v_lshl_add_u64 v[0:1], v[0:1], 2, s[8:9]
	s_mul_i32 s90, s14, 0x9000
	s_waitcnt lgkmcnt(0)
	v_lshl_add_u64 v[4:5], v[0:1], 0, s[90:91]
	s_mov_b32 s8, 0x9000
	v_add_co_u32_e64 v10, s[8:9], s8, v4
	global_load_dword v7, v[4:5], off nt
	global_load_dword v6, v[4:5], off offset:1536 nt
	global_load_dword v8, v[4:5], off offset:3072 nt
	v_addc_co_u32_e64 v11, s[8:9], 0, v5, s[8:9]
	s_mov_b32 s8, 0x12000
	global_load_dword v98, v[10:11], off nt
	global_load_dword v97, v[10:11], off offset:1536 nt
	global_load_dword v96, v[10:11], off offset:3072 nt
	v_add_co_u32_e64 v10, s[8:9], s8, v4
	s_cmp_eq_u32 s13, 0
	s_nop 0
	v_addc_co_u32_e64 v11, s[8:9], 0, v5, s[8:9]
	s_mov_b32 s8, 0x1b000
	global_load_dword v95, v[10:11], off nt
	global_load_dword v94, v[10:11], off offset:1536 nt
	global_load_dword v93, v[10:11], off offset:3072 nt
	v_add_co_u32_e64 v10, s[8:9], s8, v4
	v_readlane_b32 s25, v251, 51
	s_nop 0
	v_addc_co_u32_e64 v11, s[8:9], 0, v5, s[8:9]
	s_mov_b32 s8, 0x24000
	global_load_dword v92, v[10:11], off nt
	global_load_dword v91, v[10:11], off offset:1536 nt
	global_load_dword v90, v[10:11], off offset:3072 nt
	v_add_co_u32_e64 v10, s[8:9], s8, v4
	v_readlane_b32 s36, v251, 52
	s_nop 0
	v_addc_co_u32_e64 v11, s[8:9], 0, v5, s[8:9]
	s_mov_b32 s8, 0x2d000
	global_load_dword v89, v[10:11], off nt
	global_load_dword v88, v[10:11], off offset:1536 nt
	global_load_dword v87, v[10:11], off offset:3072 nt
	v_add_co_u32_e64 v10, s[8:9], s8, v4
	v_readlane_b32 s40, v251, 54
	s_nop 0
	v_addc_co_u32_e64 v11, s[8:9], 0, v5, s[8:9]
	s_mov_b32 s8, 0x36000
	global_load_dword v86, v[10:11], off nt
	global_load_dword v85, v[10:11], off offset:1536 nt
	global_load_dword v84, v[10:11], off offset:3072 nt
	v_add_co_u32_e64 v10, s[8:9], s8, v4
	v_readlane_b32 s37, v251, 53
	s_nop 0
	v_addc_co_u32_e64 v11, s[8:9], 0, v5, s[8:9]
	s_mov_b32 s8, 0x3f000
	global_load_dword v83, v[10:11], off nt
	global_load_dword v82, v[10:11], off offset:1536 nt
	global_load_dword v81, v[10:11], off offset:3072 nt
	v_add_co_u32_e64 v10, s[8:9], s8, v4
	v_readlane_b32 s45, v251, 5
	s_nop 0
	v_addc_co_u32_e64 v11, s[8:9], 0, v5, s[8:9]
	s_mov_b32 s8, 0x48000
	global_load_dword v80, v[10:11], off nt
	global_load_dword v79, v[10:11], off offset:1536 nt
	global_load_dword v78, v[10:11], off offset:3072 nt
	v_add_co_u32_e64 v10, s[8:9], s8, v4
	v_readlane_b32 s46, v251, 6
	s_nop 0
	v_addc_co_u32_e64 v11, s[8:9], 0, v5, s[8:9]
	s_mov_b32 s8, 0x51000
	global_load_dword v77, v[10:11], off nt
	global_load_dword v76, v[10:11], off offset:1536 nt
	global_load_dword v75, v[10:11], off offset:3072 nt
	v_add_co_u32_e64 v10, s[8:9], s8, v4
	v_readlane_b32 s47, v251, 7
	s_nop 0
	v_addc_co_u32_e64 v11, s[8:9], 0, v5, s[8:9]
	s_mov_b32 s8, 0x5a000
	global_load_dword v74, v[10:11], off nt
	global_load_dword v73, v[10:11], off offset:1536 nt
	global_load_dword v72, v[10:11], off offset:3072 nt
	v_add_co_u32_e64 v10, s[8:9], s8, v4
	v_readlane_b32 s48, v251, 8
	s_nop 0
	v_addc_co_u32_e64 v11, s[8:9], 0, v5, s[8:9]
	s_mov_b32 s8, 0x63000
	global_load_dword v71, v[10:11], off nt
	global_load_dword v70, v[10:11], off offset:1536 nt
	global_load_dword v69, v[10:11], off offset:3072 nt
	v_add_co_u32_e64 v10, s[8:9], s8, v4
	v_readlane_b32 s49, v251, 9
	s_nop 0
	v_addc_co_u32_e64 v11, s[8:9], 0, v5, s[8:9]
	s_mov_b32 s8, 0x6c000
	global_load_dword v68, v[10:11], off nt
	global_load_dword v67, v[10:11], off offset:1536 nt
	global_load_dword v66, v[10:11], off offset:3072 nt
	v_add_co_u32_e64 v10, s[8:9], s8, v4
	v_readlane_b32 s50, v251, 10
	s_nop 0
	v_addc_co_u32_e64 v11, s[8:9], 0, v5, s[8:9]
	s_mov_b32 s8, 0x75000
	global_load_dword v65, v[10:11], off nt
	global_load_dword v64, v[10:11], off offset:1536 nt
	global_load_dword v63, v[10:11], off offset:3072 nt
	v_add_co_u32_e64 v10, s[8:9], s8, v4
	v_readlane_b32 s51, v251, 11
	s_nop 0
	v_addc_co_u32_e64 v11, s[8:9], 0, v5, s[8:9]
	s_mov_b32 s8, 0x7e000
	global_load_dword v62, v[10:11], off nt
	global_load_dword v61, v[10:11], off offset:1536 nt
	global_load_dword v60, v[10:11], off offset:3072 nt
	v_add_co_u32_e64 v10, s[8:9], s8, v4
	v_readlane_b32 s52, v251, 12
	s_nop 0
	v_addc_co_u32_e64 v11, s[8:9], 0, v5, s[8:9]
	s_mov_b32 s8, 0x87000
	global_load_dword v59, v[10:11], off nt
	global_load_dword v58, v[10:11], off offset:1536 nt
	global_load_dword v57, v[10:11], off offset:3072 nt
	v_add_co_u32_e64 v10, s[8:9], s8, v4
	v_readlane_b32 s53, v251, 13
	s_nop 0
	v_addc_co_u32_e64 v11, s[8:9], 0, v5, s[8:9]
	s_mov_b32 s8, 0x90000
	global_load_dword v56, v[10:11], off nt
	global_load_dword v55, v[10:11], off offset:1536 nt
	global_load_dword v54, v[10:11], off offset:3072 nt
	v_add_co_u32_e64 v10, s[8:9], s8, v4
	v_readlane_b32 s54, v251, 14
	s_nop 0
	v_addc_co_u32_e64 v11, s[8:9], 0, v5, s[8:9]
	s_mov_b32 s8, 0x99000
	global_load_dword v53, v[10:11], off nt
	global_load_dword v52, v[10:11], off offset:1536 nt
	global_load_dword v51, v[10:11], off offset:3072 nt
	v_add_co_u32_e64 v10, s[8:9], s8, v4
	v_readlane_b32 s55, v251, 15
	s_nop 0
	v_addc_co_u32_e64 v11, s[8:9], 0, v5, s[8:9]
	s_mov_b32 s8, 0xa2000
	global_load_dword v50, v[10:11], off nt
	global_load_dword v49, v[10:11], off offset:1536 nt
	global_load_dword v48, v[10:11], off offset:3072 nt
	v_add_co_u32_e64 v10, s[8:9], s8, v4
	v_readlane_b32 s56, v251, 16
	s_nop 0
	v_addc_co_u32_e64 v11, s[8:9], 0, v5, s[8:9]
	s_mov_b32 s8, 0xab000
	global_load_dword v47, v[10:11], off nt
	global_load_dword v46, v[10:11], off offset:1536 nt
	global_load_dword v45, v[10:11], off offset:3072 nt
	v_add_co_u32_e64 v10, s[8:9], s8, v4
	v_readlane_b32 s57, v251, 17
	s_nop 0
	v_addc_co_u32_e64 v11, s[8:9], 0, v5, s[8:9]
	s_mov_b32 s8, 0xb4000
	global_load_dword v44, v[10:11], off nt
	global_load_dword v43, v[10:11], off offset:1536 nt
	global_load_dword v42, v[10:11], off offset:3072 nt
	v_add_co_u32_e64 v10, s[8:9], s8, v4
	s_nop 1
	v_addc_co_u32_e64 v11, s[8:9], 0, v5, s[8:9]
	s_mov_b32 s8, 0xbd000
	global_load_dword v41, v[10:11], off nt
	global_load_dword v40, v[10:11], off offset:1536 nt
	global_load_dword v39, v[10:11], off offset:3072 nt
	v_add_co_u32_e64 v10, s[8:9], s8, v4
	s_nop 1
	v_addc_co_u32_e64 v11, s[8:9], 0, v5, s[8:9]
	s_mov_b32 s8, 0xc6000
	global_load_dword v38, v[10:11], off nt
	global_load_dword v37, v[10:11], off offset:1536 nt
	global_load_dword v36, v[10:11], off offset:3072 nt
	v_add_co_u32_e64 v10, s[8:9], s8, v4
	s_nop 1
	v_addc_co_u32_e64 v11, s[8:9], 0, v5, s[8:9]
	s_mov_b32 s8, 0xcf000
	global_load_dword v35, v[10:11], off nt
	global_load_dword v34, v[10:11], off offset:1536 nt
	global_load_dword v33, v[10:11], off offset:3072 nt
	v_add_co_u32_e64 v10, s[8:9], s8, v4
	s_nop 1
	v_addc_co_u32_e64 v11, s[8:9], 0, v5, s[8:9]
	s_mov_b32 s8, 0xd8000
	global_load_dword v32, v[10:11], off nt
	global_load_dword v31, v[10:11], off offset:1536 nt
	global_load_dword v30, v[10:11], off offset:3072 nt
	v_add_co_u32_e64 v10, s[8:9], s8, v4
	s_nop 1
	v_addc_co_u32_e64 v11, s[8:9], 0, v5, s[8:9]
	s_mov_b32 s8, 0xe1000
	global_load_dword v29, v[10:11], off nt
	global_load_dword v28, v[10:11], off offset:1536 nt
	global_load_dword v27, v[10:11], off offset:3072 nt
	v_add_co_u32_e64 v10, s[8:9], s8, v4
	s_nop 1
	v_addc_co_u32_e64 v11, s[8:9], 0, v5, s[8:9]
	s_mov_b32 s8, 0xea000
	global_load_dword v26, v[10:11], off nt
	global_load_dword v25, v[10:11], off offset:1536 nt
	global_load_dword v24, v[10:11], off offset:3072 nt
	v_add_co_u32_e64 v10, s[8:9], s8, v4
	s_nop 1
	v_addc_co_u32_e64 v11, s[8:9], 0, v5, s[8:9]
	s_mov_b32 s8, 0xf3000
	global_load_dword v23, v[10:11], off nt
	global_load_dword v22, v[10:11], off offset:1536 nt
	global_load_dword v21, v[10:11], off offset:3072 nt
	v_add_co_u32_e64 v10, s[8:9], s8, v4
	s_nop 1
	v_addc_co_u32_e64 v11, s[8:9], 0, v5, s[8:9]
	s_mov_b32 s8, 0xfc000
	s_nop 0
	v_add_co_u32_e64 v12, s[8:9], s8, v4
	global_load_dword v20, v[10:11], off nt
	global_load_dword v19, v[10:11], off offset:1536 nt
	global_load_dword v18, v[10:11], off offset:3072 nt
	v_addc_co_u32_e64 v13, s[8:9], 0, v5, s[8:9]
	s_mov_b32 s8, 0x105000
	global_load_dword v17, v[12:13], off nt
	global_load_dword v11, v[12:13], off offset:1536 nt
	global_load_dword v10, v[12:13], off offset:3072 nt
	v_add_co_u32_e64 v12, s[8:9], s8, v4
	s_nop 1
	v_addc_co_u32_e64 v13, s[8:9], 0, v5, s[8:9]
	s_mov_b32 s8, 0x10e000
	s_nop 0
	v_add_co_u32_e64 v100, s[8:9], s8, v4
	global_load_dword v16, v[12:13], off nt
	global_load_dword v15, v[12:13], off offset:1536 nt
	global_load_dword v14, v[12:13], off offset:3072 nt
	v_addc_co_u32_e64 v101, s[8:9], 0, v5, s[8:9]
	s_cselect_b64 s[8:9], -1, 0
	s_ashr_i32 s13, s12, 31
	s_lshl_b64 s[14:15], s[12:13], 2
	s_add_u32 s16, s67, s14
	s_addc_u32 s17, s25, s15
	global_load_dword v13, v[100:101], off nt
	global_load_dword v12, v[100:101], off offset:1536 nt
	global_load_dword v3, v[100:101], off offset:3072 nt
	global_load_dword v9, v181, s[16:17]
	s_add_u32 s16, s34, s14
	s_addc_u32 s17, s36, s15
	global_load_dword v99, v181, s[16:17]
	s_and_b64 s[8:9], s[8:9], s[6:7]
	global_store_dword v[4:5], v181, off
	global_store_dword v[4:5], v181, off offset:1536
	global_store_dword v[4:5], v181, off offset:3072
	s_and_saveexec_b64 s[16:17], s[8:9]
	s_cbranch_execz .LBB0_369
	s_add_u32 s14, s37, s14
	s_addc_u32 s15, s40, s15
	global_store_dword v181, v181, s[14:15]

.LBB0_598:
	v_lshl_add_u32 v162, s65, 8, v3
	v_lshl_or_b32 v178, s68, 8, v171
	v_ashrrev_i32_e32 v179, 31, v178
	v_ashrrev_i32_e32 v163, 31, v162
	v_lshl_add_u64 v[160:161], v[178:179], 1, s[42:43]
	v_lshlrev_b64 v[132:133], 11, v[162:163]
	v_lshl_add_u64 v[132:133], v[160:161], 0, v[132:133]
	global_load_dwordx4 v[174:177], v[132:133], off nt
	global_load_dwordx4 v[190:193], v[132:133], off offset:256 nt
	v_or_b32_e32 v168, 16, v162
	v_ashrrev_i32_e32 v169, 31, v168
	v_lshlrev_b64 v[132:133], 11, v[168:169]
	v_lshl_add_u64 v[132:133], v[160:161], 0, v[132:133]
	global_load_dwordx4 v[194:197], v[132:133], off nt
	global_load_dwordx4 v[148:151], v[132:133], off offset:256 nt
	v_or_b32_e32 v166, 32, v162
	v_ashrrev_i32_e32 v167, 31, v166
	v_lshlrev_b64 v[132:133], 11, v[166:167]
	v_lshl_add_u64 v[132:133], v[160:161], 0, v[132:133]
	global_load_dwordx4 v[144:147], v[132:133], off nt
	global_load_dwordx4 v[140:143], v[132:133], off offset:256 nt
	v_or_b32_e32 v164, 48, v162
	v_ashrrev_i32_e32 v165, 31, v164
	v_lshlrev_b64 v[132:133], 11, v[164:165]
	v_lshl_add_u64 v[132:133], v[160:161], 0, v[132:133]
	global_load_dwordx4 v[136:139], v[132:133], off nt
	s_nop 0
	global_load_dwordx4 v[132:135], v[132:133], off offset:256 nt
	v_readlane_b32 s68, v251, 4
	v_readlane_b32 s82, v251, 18
	v_readlane_b32 s83, v251, 19
	s_mov_b64 s[26:27], -1
	s_and_b64 vcc, exec, s[6:7]
	v_readlane_b32 s69, v251, 5
	v_readlane_b32 s70, v251, 6
	v_readlane_b32 s71, v251, 7
	v_readlane_b32 s72, v251, 8
	v_readlane_b32 s73, v251, 9
	v_readlane_b32 s74, v251, 10
	v_readlane_b32 s75, v251, 11
	v_readlane_b32 s76, v251, 12
	v_readlane_b32 s77, v251, 13
	v_readlane_b32 s78, v251, 14
	v_readlane_b32 s79, v251, 15
	v_readlane_b32 s80, v251, 16
	v_readlane_b32 s81, v251, 17
	s_waitcnt vmcnt(0)
	v_lshlrev_b32_e32 v182, 16, v174
	v_and_b32_e32 v183, 0xffff0000, v174
	v_lshlrev_b32_e32 v174, 16, v175
	v_and_b32_e32 v175, 0xffff0000, v175
	v_lshlrev_b32_e32 v184, 16, v176
	v_and_b32_e32 v185, 0xffff0000, v176
	v_lshlrev_b32_e32 v176, 16, v177
	v_and_b32_e32 v177, 0xffff0000, v177
	v_pk_fma_f32 v[130:131], v[130:131], 0.5, v[174:175] op_sel_hi:[1,0,1]
	v_pk_fma_f32 v[174:175], v[124:125], 0.5, v[184:185] op_sel_hi:[1,0,1]
	v_lshlrev_b64 v[124:125], 12, v[162:163]
	v_pk_fma_f32 v[176:177], v[126:127], 0.5, v[176:177] op_sel_hi:[1,0,1]
	v_lshl_add_u64 v[126:127], s[82:83], 0, v[124:125]
	v_lshlrev_b64 v[124:125], 2, v[178:179]
	v_pk_fma_f32 v[128:129], v[128:129], 0.5, v[182:183] op_sel_hi:[1,0,1]
	v_lshl_add_u64 v[126:127], v[126:127], 0, v[124:125]
	global_store_dwordx4 v[126:127], v[128:131], off
	global_store_dwordx4 v[126:127], v[174:177], off offset:16
	s_nop 0
	v_lshlrev_b32_e32 v128, 16, v190
	v_and_b32_e32 v129, 0xffff0000, v190
	v_lshlrev_b32_e32 v130, 16, v191
	v_and_b32_e32 v131, 0xffff0000, v191
	v_lshlrev_b32_e32 v174, 16, v192
	v_and_b32_e32 v175, 0xffff0000, v192
	v_lshlrev_b32_e32 v176, 16, v193
	v_and_b32_e32 v177, 0xffff0000, v193
	v_pk_fma_f32 v[114:115], v[114:115], 0.5, v[130:131] op_sel_hi:[1,0,1]
	v_pk_fma_f32 v[112:113], v[112:113], 0.5, v[128:129] op_sel_hi:[1,0,1]
	v_pk_fma_f32 v[110:111], v[110:111], 0.5, v[176:177] op_sel_hi:[1,0,1]
	v_pk_fma_f32 v[108:109], v[108:109], 0.5, v[174:175] op_sel_hi:[1,0,1]
	global_store_dwordx4 v[126:127], v[112:115], off offset:512
	global_store_dwordx4 v[126:127], v[108:111], off offset:528
	s_nop 0
	v_lshlrev_b32_e32 v112, 16, v196
	v_and_b32_e32 v113, 0xffff0000, v196
	v_pk_fma_f32 v[112:113], v[116:117], 0.5, v[112:113] op_sel_hi:[1,0,1]
	v_lshlrev_b64 v[116:117], 12, v[168:169]
	v_lshlrev_b32_e32 v108, 16, v194
	v_and_b32_e32 v109, 0xffff0000, v194
	v_lshlrev_b32_e32 v110, 16, v195
	v_and_b32_e32 v111, 0xffff0000, v195
	v_lshl_add_u64 v[116:117], s[82:83], 0, v[116:117]
	v_lshlrev_b32_e32 v114, 16, v197
	v_and_b32_e32 v115, 0xffff0000, v197
	v_pk_fma_f32 v[110:111], v[122:123], 0.5, v[110:111] op_sel_hi:[1,0,1]
	v_pk_fma_f32 v[108:109], v[120:121], 0.5, v[108:109] op_sel_hi:[1,0,1]
	v_lshl_add_u64 v[116:117], v[116:117], 0, v[124:125]
	v_pk_fma_f32 v[114:115], v[118:119], 0.5, v[114:115] op_sel_hi:[1,0,1]
	global_store_dwordx4 v[116:117], v[108:111], off
	global_store_dwordx4 v[116:117], v[112:115], off offset:16
	s_nop 0
	v_lshlrev_b32_e32 v108, 16, v148
	v_and_b32_e32 v109, 0xffff0000, v148
	v_lshlrev_b32_e32 v110, 16, v149
	v_and_b32_e32 v111, 0xffff0000, v149
	v_lshlrev_b32_e32 v112, 16, v150
	v_and_b32_e32 v113, 0xffff0000, v150
	v_lshlrev_b32_e32 v114, 16, v151
	v_and_b32_e32 v115, 0xffff0000, v151
	v_pk_fma_f32 v[106:107], v[106:107], 0.5, v[110:111] op_sel_hi:[1,0,1]
	v_pk_fma_f32 v[104:105], v[104:105], 0.5, v[108:109] op_sel_hi:[1,0,1]
	v_pk_fma_f32 v[100:101], v[100:101], 0.5, v[112:113] op_sel_hi:[1,0,1]
	v_pk_fma_f32 v[102:103], v[102:103], 0.5, v[114:115] op_sel_hi:[1,0,1]
	global_store_dwordx4 v[116:117], v[104:107], off offset:512
	global_store_dwordx4 v[116:117], v[100:103], off offset:528
	s_nop 0
	v_lshlrev_b32_e32 v104, 16, v146
	v_lshlrev_b32_e32 v100, 16, v144
	v_and_b32_e32 v101, 0xffff0000, v144
	v_pk_fma_f32 v[96:97], v[96:97], 0.5, v[100:101] op_sel_hi:[1,0,1]
	v_lshlrev_b64 v[100:101], 12, v[166:167]
	v_lshlrev_b32_e32 v102, 16, v145
	v_and_b32_e32 v103, 0xffff0000, v145
	v_and_b32_e32 v105, 0xffff0000, v146
	v_lshlrev_b32_e32 v106, 16, v147
	v_and_b32_e32 v107, 0xffff0000, v147
	v_lshl_add_u64 v[100:101], s[82:83], 0, v[100:101]
	v_pk_fma_f32 v[98:99], v[98:99], 0.5, v[102:103] op_sel_hi:[1,0,1]
	v_pk_fma_f32 v[94:95], v[94:95], 0.5, v[106:107] op_sel_hi:[1,0,1]
	v_pk_fma_f32 v[92:93], v[92:93], 0.5, v[104:105] op_sel_hi:[1,0,1]
	v_lshl_add_u64 v[100:101], v[100:101], 0, v[124:125]
	global_store_dwordx4 v[100:101], v[96:99], off
	global_store_dwordx4 v[100:101], v[92:95], off offset:16
	v_add_u32_e32 v102, 0x90, v162
	v_lshlrev_b32_e32 v96, 16, v142
	v_lshlrev_b32_e32 v92, 16, v140
	v_and_b32_e32 v93, 0xffff0000, v140
	v_lshlrev_b32_e32 v94, 16, v141
	v_and_b32_e32 v95, 0xffff0000, v141
	v_and_b32_e32 v97, 0xffff0000, v142
	v_lshlrev_b32_e32 v98, 16, v143
	v_and_b32_e32 v99, 0xffff0000, v143
	v_pk_fma_f32 v[90:91], v[90:91], 0.5, v[94:95] op_sel_hi:[1,0,1]
	v_pk_fma_f32 v[88:89], v[88:89], 0.5, v[92:93] op_sel_hi:[1,0,1]
	v_pk_fma_f32 v[80:81], v[80:81], 0.5, v[96:97] op_sel_hi:[1,0,1]
	v_pk_fma_f32 v[82:83], v[82:83], 0.5, v[98:99] op_sel_hi:[1,0,1]
	global_store_dwordx4 v[100:101], v[88:91], off offset:512
	global_store_dwordx4 v[100:101], v[80:83], off offset:528
	v_add_u32_e32 v100, 0x80, v162
	v_lshlrev_b32_e32 v88, 16, v138
	v_lshlrev_b32_e32 v80, 16, v136
	v_and_b32_e32 v81, 0xffff0000, v136
	v_pk_fma_f32 v[80:81], v[84:85], 0.5, v[80:81] op_sel_hi:[1,0,1]
	v_lshlrev_b64 v[84:85], 12, v[164:165]
	v_lshlrev_b32_e32 v82, 16, v137
	v_and_b32_e32 v83, 0xffff0000, v137
	v_and_b32_e32 v89, 0xffff0000, v138
	v_lshlrev_b32_e32 v90, 16, v139
	v_and_b32_e32 v91, 0xffff0000, v139
	v_lshl_add_u64 v[84:85], s[82:83], 0, v[84:85]
	v_pk_fma_f32 v[82:83], v[86:87], 0.5, v[82:83] op_sel_hi:[1,0,1]
	v_pk_fma_f32 v[78:79], v[78:79], 0.5, v[90:91] op_sel_hi:[1,0,1]
	v_pk_fma_f32 v[76:77], v[76:77], 0.5, v[88:89] op_sel_hi:[1,0,1]
	v_lshl_add_u64 v[84:85], v[84:85], 0, v[124:125]
	global_store_dwordx4 v[84:85], v[80:83], off
	global_store_dwordx4 v[84:85], v[76:79], off offset:16
	v_ashrrev_i32_e32 v101, 31, v100
	v_lshlrev_b32_e32 v80, 16, v134
	v_lshlrev_b32_e32 v76, 16, v132
	v_and_b32_e32 v77, 0xffff0000, v132
	v_lshlrev_b32_e32 v78, 16, v133
	v_and_b32_e32 v79, 0xffff0000, v133
	v_and_b32_e32 v81, 0xffff0000, v134
	v_lshlrev_b32_e32 v82, 16, v135
	v_and_b32_e32 v83, 0xffff0000, v135
	v_pk_fma_f32 v[74:75], v[74:75], 0.5, v[78:79] op_sel_hi:[1,0,1]
	v_pk_fma_f32 v[72:73], v[72:73], 0.5, v[76:77] op_sel_hi:[1,0,1]
	v_pk_fma_f32 v[68:69], v[68:69], 0.5, v[80:81] op_sel_hi:[1,0,1]
	v_pk_fma_f32 v[70:71], v[70:71], 0.5, v[82:83] op_sel_hi:[1,0,1]
	global_store_dwordx4 v[84:85], v[72:75], off offset:512
	global_store_dwordx4 v[84:85], v[68:71], off offset:528
	v_ashrrev_i32_e32 v103, 31, v102
	v_add_u32_e32 v104, 0xa0, v162
	v_lshlrev_b64 v[68:69], 11, v[100:101]
	v_lshl_add_u64 v[68:69], v[160:161], 0, v[68:69]
	global_load_dwordx4 v[72:75], v[68:69], off nt
	global_load_dwordx4 v[76:79], v[68:69], off offset:256 nt
	v_lshlrev_b64 v[68:69], 11, v[102:103]
	v_lshl_add_u64 v[68:69], v[160:161], 0, v[68:69]
	global_load_dwordx4 v[80:83], v[68:69], off nt
	global_load_dwordx4 v[84:87], v[68:69], off offset:256 nt
	v_ashrrev_i32_e32 v105, 31, v104
	v_lshlrev_b64 v[68:69], 11, v[104:105]
	v_lshl_add_u64 v[68:69], v[160:161], 0, v[68:69]
	global_load_dwordx4 v[88:91], v[68:69], off nt
	global_load_dwordx4 v[92:95], v[68:69], off offset:256 nt
	v_add_u32_e32 v106, 0xb0, v162
	v_ashrrev_i32_e32 v107, 31, v106
	v_lshlrev_b64 v[68:69], 11, v[106:107]
	v_lshl_add_u64 v[68:69], v[160:161], 0, v[68:69]
	global_load_dwordx4 v[96:99], v[68:69], off nt
	s_nop 0
	global_load_dwordx4 v[68:71], v[68:69], off offset:256 nt
	s_waitcnt vmcnt(7)
	v_lshlrev_b32_e32 v108, 16, v72
	v_and_b32_e32 v109, 0xffff0000, v72
	v_lshlrev_b32_e32 v72, 16, v73
	v_and_b32_e32 v73, 0xffff0000, v73
	v_pk_fma_f32 v[66:67], v[66:67], 0.5, v[72:73] op_sel_hi:[1,0,1]
	v_lshlrev_b64 v[72:73], 12, v[100:101]
	v_lshlrev_b32_e32 v110, 16, v74
	v_and_b32_e32 v111, 0xffff0000, v74
	v_lshlrev_b32_e32 v74, 16, v75
	v_and_b32_e32 v75, 0xffff0000, v75
	v_lshl_add_u64 v[72:73], s[82:83], 0, v[72:73]
	v_pk_fma_f32 v[64:65], v[64:65], 0.5, v[108:109] op_sel_hi:[1,0,1]
	v_pk_fma_f32 v[62:63], v[62:63], 0.5, v[74:75] op_sel_hi:[1,0,1]
	v_pk_fma_f32 v[60:61], v[60:61], 0.5, v[110:111] op_sel_hi:[1,0,1]
	v_lshl_add_u64 v[72:73], v[72:73], 0, v[124:125]
	global_store_dwordx4 v[72:73], v[64:67], off
	global_store_dwordx4 v[72:73], v[60:63], off offset:16
	s_waitcnt vmcnt(8)
	v_lshlrev_b32_e32 v64, 16, v78
	v_lshlrev_b32_e32 v60, 16, v76
	v_and_b32_e32 v61, 0xffff0000, v76
	v_lshlrev_b32_e32 v62, 16, v77
	v_and_b32_e32 v63, 0xffff0000, v77
	v_and_b32_e32 v65, 0xffff0000, v78
	v_lshlrev_b32_e32 v66, 16, v79
	v_and_b32_e32 v67, 0xffff0000, v79
	v_pk_fma_f32 v[58:59], v[58:59], 0.5, v[62:63] op_sel_hi:[1,0,1]
	v_pk_fma_f32 v[56:57], v[56:57], 0.5, v[60:61] op_sel_hi:[1,0,1]
	v_pk_fma_f32 v[48:49], v[48:49], 0.5, v[64:65] op_sel_hi:[1,0,1]
	v_pk_fma_f32 v[50:51], v[50:51], 0.5, v[66:67] op_sel_hi:[1,0,1]
	global_store_dwordx4 v[72:73], v[56:59], off offset:512
	global_store_dwordx4 v[72:73], v[48:51], off offset:528
	s_waitcnt vmcnt(9)
	v_lshlrev_b32_e32 v56, 16, v82
	v_lshlrev_b32_e32 v48, 16, v80
	v_and_b32_e32 v49, 0xffff0000, v80
	v_pk_fma_f32 v[48:49], v[52:53], 0.5, v[48:49] op_sel_hi:[1,0,1]
	v_lshlrev_b64 v[52:53], 12, v[102:103]
	v_lshlrev_b32_e32 v50, 16, v81
	v_and_b32_e32 v51, 0xffff0000, v81
	v_and_b32_e32 v57, 0xffff0000, v82
	v_lshlrev_b32_e32 v58, 16, v83
	v_and_b32_e32 v59, 0xffff0000, v83
	v_lshl_add_u64 v[52:53], s[82:83], 0, v[52:53]
	v_pk_fma_f32 v[50:51], v[54:55], 0.5, v[50:51] op_sel_hi:[1,0,1]
	v_pk_fma_f32 v[46:47], v[46:47], 0.5, v[58:59] op_sel_hi:[1,0,1]
	v_pk_fma_f32 v[44:45], v[44:45], 0.5, v[56:57] op_sel_hi:[1,0,1]
	v_lshl_add_u64 v[52:53], v[52:53], 0, v[124:125]
	global_store_dwordx4 v[52:53], v[48:51], off
	global_store_dwordx4 v[52:53], v[44:47], off offset:16
	s_waitcnt vmcnt(10)
	v_lshlrev_b32_e32 v48, 16, v86
	v_lshlrev_b32_e32 v44, 16, v84
	v_and_b32_e32 v45, 0xffff0000, v84
	v_lshlrev_b32_e32 v46, 16, v85
	v_and_b32_e32 v47, 0xffff0000, v85
	v_and_b32_e32 v49, 0xffff0000, v86
	v_lshlrev_b32_e32 v50, 16, v87
	v_and_b32_e32 v51, 0xffff0000, v87
	v_pk_fma_f32 v[42:43], v[42:43], 0.5, v[46:47] op_sel_hi:[1,0,1]
	v_pk_fma_f32 v[40:41], v[40:41], 0.5, v[44:45] op_sel_hi:[1,0,1]
	v_pk_fma_f32 v[32:33], v[32:33], 0.5, v[48:49] op_sel_hi:[1,0,1]
	v_pk_fma_f32 v[34:35], v[34:35], 0.5, v[50:51] op_sel_hi:[1,0,1]
	global_store_dwordx4 v[52:53], v[40:43], off offset:512
	global_store_dwordx4 v[52:53], v[32:35], off offset:528
	s_waitcnt vmcnt(11)
	v_lshlrev_b32_e32 v40, 16, v90
	v_lshlrev_b32_e32 v32, 16, v88
	v_and_b32_e32 v33, 0xffff0000, v88
	v_pk_fma_f32 v[32:33], v[36:37], 0.5, v[32:33] op_sel_hi:[1,0,1]
	v_lshlrev_b64 v[36:37], 12, v[104:105]
	v_lshlrev_b32_e32 v34, 16, v89
	v_and_b32_e32 v35, 0xffff0000, v89
	v_and_b32_e32 v41, 0xffff0000, v90
	v_lshlrev_b32_e32 v42, 16, v91
	v_and_b32_e32 v43, 0xffff0000, v91
	v_lshl_add_u64 v[36:37], s[82:83], 0, v[36:37]
	v_pk_fma_f32 v[34:35], v[38:39], 0.5, v[34:35] op_sel_hi:[1,0,1]
	v_pk_fma_f32 v[30:31], v[30:31], 0.5, v[42:43] op_sel_hi:[1,0,1]
	v_pk_fma_f32 v[28:29], v[28:29], 0.5, v[40:41] op_sel_hi:[1,0,1]
	v_lshl_add_u64 v[36:37], v[36:37], 0, v[124:125]
	global_store_dwordx4 v[36:37], v[32:35], off
	global_store_dwordx4 v[36:37], v[28:31], off offset:16
	s_waitcnt vmcnt(12)
	v_lshlrev_b32_e32 v32, 16, v94
	v_lshlrev_b32_e32 v28, 16, v92
	v_and_b32_e32 v29, 0xffff0000, v92
	v_lshlrev_b32_e32 v30, 16, v93
	v_and_b32_e32 v31, 0xffff0000, v93
	v_and_b32_e32 v33, 0xffff0000, v94
	v_lshlrev_b32_e32 v34, 16, v95
	v_and_b32_e32 v35, 0xffff0000, v95
	v_pk_fma_f32 v[26:27], v[26:27], 0.5, v[30:31] op_sel_hi:[1,0,1]
	v_pk_fma_f32 v[24:25], v[24:25], 0.5, v[28:29] op_sel_hi:[1,0,1]
	v_pk_fma_f32 v[16:17], v[16:17], 0.5, v[32:33] op_sel_hi:[1,0,1]
	v_pk_fma_f32 v[18:19], v[18:19], 0.5, v[34:35] op_sel_hi:[1,0,1]
	global_store_dwordx4 v[36:37], v[24:27], off offset:512
	global_store_dwordx4 v[36:37], v[16:19], off offset:528
	s_waitcnt vmcnt(13)
	v_lshlrev_b32_e32 v24, 16, v98
	v_lshlrev_b32_e32 v16, 16, v96
	v_and_b32_e32 v17, 0xffff0000, v96
	v_pk_fma_f32 v[16:17], v[20:21], 0.5, v[16:17] op_sel_hi:[1,0,1]
	v_lshlrev_b64 v[20:21], 12, v[106:107]
	v_lshlrev_b32_e32 v18, 16, v97
	v_and_b32_e32 v19, 0xffff0000, v97
	v_and_b32_e32 v25, 0xffff0000, v98
	v_lshlrev_b32_e32 v26, 16, v99
	v_and_b32_e32 v27, 0xffff0000, v99
	v_lshl_add_u64 v[20:21], s[82:83], 0, v[20:21]
	v_pk_fma_f32 v[18:19], v[22:23], 0.5, v[18:19] op_sel_hi:[1,0,1]
	v_pk_fma_f32 v[14:15], v[14:15], 0.5, v[26:27] op_sel_hi:[1,0,1]
	v_pk_fma_f32 v[12:13], v[12:13], 0.5, v[24:25] op_sel_hi:[1,0,1]
	v_lshl_add_u64 v[20:21], v[20:21], 0, v[124:125]
	global_store_dwordx4 v[20:21], v[16:19], off
	global_store_dwordx4 v[20:21], v[12:15], off offset:16
	s_waitcnt vmcnt(14)
	v_lshlrev_b32_e32 v16, 16, v70
	v_lshlrev_b32_e32 v12, 16, v68
	v_and_b32_e32 v13, 0xffff0000, v68
	v_lshlrev_b32_e32 v14, 16, v69
	v_and_b32_e32 v15, 0xffff0000, v69
	v_and_b32_e32 v17, 0xffff0000, v70
	v_lshlrev_b32_e32 v18, 16, v71
	v_and_b32_e32 v19, 0xffff0000, v71
	v_pk_fma_f32 v[10:11], v[10:11], 0.5, v[14:15] op_sel_hi:[1,0,1]
	v_pk_fma_f32 v[8:9], v[8:9], 0.5, v[12:13] op_sel_hi:[1,0,1]
	v_pk_fma_f32 v[6:7], v[6:7], 0.5, v[18:19] op_sel_hi:[1,0,1]
	v_pk_fma_f32 v[4:5], v[4:5], 0.5, v[16:17] op_sel_hi:[1,0,1]
	global_store_dwordx4 v[20:21], v[8:11], off offset:512
	global_store_dwordx4 v[20:21], v[4:7], off offset:528
	s_waitcnt lgkmcnt(0)
	s_barrier
	s_cbranch_vccnz .LBB0_583
	s_andn2_b64 vcc, exec, s[14:15]
	s_cbranch_vccnz .LBB0_582
	s_barrier
	s_branch .LBB0_582

.LBB0_627:
	v_and_b32_e32 v133, 64, v216
	v_xor_b32_e32 v132, 16, v216
	v_add_u32_e32 v133, 64, v133
	v_cmp_lt_i32_e32 vcc, v132, v133
	s_lshl_b32 s27, s27, 8
	v_lshl_or_b32 v170, s26, 8, v192
	v_cndmask_b32_e32 v132, v216, v132, vcc
	v_add_u32_e32 v172, s27, v3
	v_ashrrev_i32_e32 v171, 31, v170
	v_lshlrev_b32_e32 v195, 2, v132
	v_xor_b32_e32 v132, 32, v216
	v_cmp_lt_i32_e32 vcc, v132, v133
	v_lshlrev_b64 v[182:183], 1, v[170:171]
	v_ashrrev_i32_e32 v173, 31, v172
	v_cndmask_b32_e32 v132, v216, v132, vcc
	v_lshl_add_u64 v[174:175], s[42:43], 0, v[182:183]
	v_lshlrev_b64 v[184:185], 11, v[172:173]
	v_lshlrev_b32_e32 v180, 2, v132
	v_lshl_add_u64 v[132:133], v[174:175], 0, v[184:185]
	global_load_dwordx4 v[196:199], v[132:133], off nt
	global_load_dwordx4 v[156:159], v[132:133], off offset:256 nt
	v_or_b32_e32 v132, 16, v172
	v_ashrrev_i32_e32 v133, 31, v132
	v_lshlrev_b64 v[190:191], 11, v[132:133]
	v_lshl_add_u64 v[132:133], v[174:175], 0, v[190:191]
	global_load_dwordx4 v[152:155], v[132:133], off nt
	global_load_dwordx4 v[148:151], v[132:133], off offset:256 nt
	v_or_b32_e32 v132, 32, v172
	v_ashrrev_i32_e32 v133, 31, v132
	v_lshlrev_b64 v[178:179], 11, v[132:133]
	v_lshl_add_u64 v[132:133], v[174:175], 0, v[178:179]
	global_load_dwordx4 v[144:147], v[132:133], off nt
	global_load_dwordx4 v[140:143], v[132:133], off offset:256 nt
	v_or_b32_e32 v132, 48, v172
	v_ashrrev_i32_e32 v133, 31, v132
	v_lshlrev_b64 v[176:177], 11, v[132:133]
	v_lshl_add_u64 v[132:133], v[174:175], 0, v[176:177]
	global_load_dwordx4 v[136:139], v[132:133], off nt
	s_nop 0
	global_load_dwordx4 v[132:135], v[132:133], off offset:256 nt
	s_waitcnt vmcnt(0)
	v_lshlrev_b32_e32 v200, 16, v196
	v_and_b32_e32 v201, 0xffff0000, v196
	v_lshlrev_b32_e32 v196, 16, v197
	v_and_b32_e32 v197, 0xffff0000, v197
	v_lshlrev_b32_e32 v202, 16, v198
	v_and_b32_e32 v203, 0xffff0000, v198
	v_lshlrev_b32_e32 v198, 16, v199
	v_and_b32_e32 v199, 0xffff0000, v199
	v_pk_fma_f32 v[130:131], v[130:131], 0.5, v[196:197] op_sel_hi:[1,0,1]
	v_pk_fma_f32 v[128:129], v[128:129], 0.5, v[200:201] op_sel_hi:[1,0,1]
	v_pk_fma_f32 v[196:197], v[126:127], 0.5, v[198:199] op_sel_hi:[1,0,1]
	v_mul_f32_e32 v126, v129, v129
	v_mul_f32_e32 v127, v131, v131
	v_pk_fma_f32 v[124:125], v[124:125], 0.5, v[202:203] op_sel_hi:[1,0,1]
	v_fmac_f32_e32 v126, v128, v128
	v_fmac_f32_e32 v127, v130, v130
	v_add_f32_e32 v126, v126, v127
	v_mul_f32_e32 v127, v125, v125
	v_fmac_f32_e32 v127, v124, v124
	v_add_f32_e32 v126, v127, v126
	v_mul_f32_e32 v127, v197, v197
	v_fmac_f32_e32 v127, v196, v196
	v_add_f32_e32 v198, v127, v126
	v_cvt_pk_bf16_f32 v126, v128, v129
	v_cvt_pk_bf16_f32 v128, v124, v125
	v_lshl_add_u64 v[124:125], s[42:43], 0, v[184:185]
	v_cvt_pk_bf16_f32 v127, v130, v131
	v_cvt_pk_bf16_f32 v129, v196, v197
	v_lshl_add_u64 v[124:125], v[124:125], 0, v[182:183]
	global_store_dwordx4 v[124:125], v[126:129], off
	v_lshlrev_b32_e32 v130, 16, v158
	v_and_b32_e32 v131, 0xffff0000, v158
	v_lshlrev_b32_e32 v126, 16, v156
	v_and_b32_e32 v127, 0xffff0000, v156
	v_lshlrev_b32_e32 v128, 16, v157
	v_and_b32_e32 v129, 0xffff0000, v157
	v_lshlrev_b32_e32 v156, 16, v159
	v_and_b32_e32 v157, 0xffff0000, v159
	v_pk_fma_f32 v[122:123], v[122:123], 0.5, v[128:129] op_sel_hi:[1,0,1]
	v_pk_fma_f32 v[120:121], v[120:121], 0.5, v[126:127] op_sel_hi:[1,0,1]
	v_pk_fma_f32 v[126:127], v[118:119], 0.5, v[156:157] op_sel_hi:[1,0,1]
	v_pk_fma_f32 v[118:119], v[116:117], 0.5, v[130:131] op_sel_hi:[1,0,1]
	v_mul_f32_e32 v116, v121, v121
	v_mul_f32_e32 v117, v123, v123
	v_fmac_f32_e32 v116, v120, v120
	v_fmac_f32_e32 v117, v122, v122
	v_add_f32_e32 v116, v116, v117
	v_mul_f32_e32 v117, v119, v119
	v_fmac_f32_e32 v117, v118, v118
	v_add_f32_e32 v116, v117, v116
	v_mul_f32_e32 v117, v127, v127
	v_fmac_f32_e32 v117, v126, v126
	v_add_f32_e32 v116, v117, v116
	v_add_f32_e32 v128, v198, v116
	v_cvt_pk_bf16_f32 v116, v120, v121
	v_cvt_pk_bf16_f32 v117, v122, v123
	v_cvt_pk_bf16_f32 v118, v118, v119
	v_cvt_pk_bf16_f32 v119, v126, v127
	global_store_dwordx4 v[124:125], v[116:119], off offset:256
	ds_bpermute_b32 v116, v195, v128
	s_waitcnt lgkmcnt(0)
	v_add_f32_e32 v116, v128, v116
	ds_bpermute_b32 v117, v180, v116
	s_and_saveexec_b64 s[44:45], s[8:9]
	s_cbranch_execz .LBB0_629
	s_waitcnt lgkmcnt(0)
	v_add_f32_e32 v116, v116, v117
	ds_write_b32 v193, v116

.LBB0_635:
	s_or_b64 exec, exec, s[44:45]
	s_waitcnt lgkmcnt(0)
	v_lshlrev_b64 v[68:69], 11, v[172:173]
	s_mov_b64 s[40:41], 0x40000
	v_lshl_add_u64 v[106:107], v[68:69], 0, s[40:41]
	v_lshl_add_u64 v[70:71], v[174:175], 0, v[106:107]
	global_load_dwordx4 v[98:101], v[70:71], off nt
	global_load_dwordx4 v[102:105], v[70:71], off offset:256 nt
	s_mov_b64 s[40:41], 0x48000
	v_lshl_add_u64 v[96:97], v[68:69], 0, s[40:41]
	s_mov_b64 s[40:41], 0x50000
	v_lshl_add_u64 v[94:95], v[68:69], 0, s[40:41]
	s_mov_b64 s[40:41], 0x58000
	v_lshl_add_u64 v[70:71], v[174:175], 0, v[96:97]
	v_lshl_add_u64 v[92:93], v[68:69], 0, s[40:41]
	global_load_dwordx4 v[88:91], v[70:71], off nt
	global_load_dwordx4 v[84:87], v[70:71], off offset:256 nt
	v_lshl_add_u64 v[70:71], v[174:175], 0, v[94:95]
	v_lshl_add_u64 v[68:69], v[174:175], 0, v[92:93]
	global_load_dwordx4 v[80:83], v[70:71], off nt
	global_load_dwordx4 v[76:79], v[70:71], off offset:256 nt
	global_load_dwordx4 v[72:75], v[68:69], off nt
	s_nop 0
	global_load_dwordx4 v[68:71], v[68:69], off offset:256 nt
	s_waitcnt vmcnt(7)
	v_lshlrev_b32_e32 v108, 16, v98
	v_and_b32_e32 v109, 0xffff0000, v98
	v_lshlrev_b32_e32 v98, 16, v99
	v_and_b32_e32 v99, 0xffff0000, v99
	v_lshlrev_b32_e32 v110, 16, v100
	v_and_b32_e32 v111, 0xffff0000, v100
	v_lshlrev_b32_e32 v100, 16, v101
	v_and_b32_e32 v101, 0xffff0000, v101
	v_pk_fma_f32 v[66:67], v[66:67], 0.5, v[98:99] op_sel_hi:[1,0,1]
	v_pk_fma_f32 v[64:65], v[64:65], 0.5, v[108:109] op_sel_hi:[1,0,1]
	v_pk_fma_f32 v[98:99], v[62:63], 0.5, v[100:101] op_sel_hi:[1,0,1]
	v_mul_f32_e32 v62, v65, v65
	v_mul_f32_e32 v63, v67, v67
	v_pk_fma_f32 v[60:61], v[60:61], 0.5, v[110:111] op_sel_hi:[1,0,1]
	v_fmac_f32_e32 v62, v64, v64
	v_fmac_f32_e32 v63, v66, v66
	v_add_f32_e32 v62, v62, v63
	v_mul_f32_e32 v63, v61, v61
	v_fmac_f32_e32 v63, v60, v60
	v_add_f32_e32 v62, v63, v62
	v_mul_f32_e32 v63, v99, v99
	v_fmac_f32_e32 v63, v98, v98
	v_add_f32_e32 v100, v63, v62
	v_cvt_pk_bf16_f32 v62, v64, v65
	v_cvt_pk_bf16_f32 v64, v60, v61
	v_lshl_add_u64 v[60:61], s[42:43], 0, v[106:107]
	v_cvt_pk_bf16_f32 v63, v66, v67
	v_cvt_pk_bf16_f32 v65, v98, v99
	v_lshl_add_u64 v[60:61], v[170:171], 1, v[60:61]
	global_store_dwordx4 v[60:61], v[62:65], off
	s_waitcnt vmcnt(7)
	v_lshlrev_b32_e32 v66, 16, v104
	v_and_b32_e32 v67, 0xffff0000, v104
	v_lshlrev_b32_e32 v62, 16, v102
	v_and_b32_e32 v63, 0xffff0000, v102
	v_lshlrev_b32_e32 v64, 16, v103
	v_and_b32_e32 v65, 0xffff0000, v103
	v_lshlrev_b32_e32 v98, 16, v105
	v_and_b32_e32 v99, 0xffff0000, v105
	v_pk_fma_f32 v[58:59], v[58:59], 0.5, v[64:65] op_sel_hi:[1,0,1]
	v_pk_fma_f32 v[56:57], v[56:57], 0.5, v[62:63] op_sel_hi:[1,0,1]
	v_pk_fma_f32 v[62:63], v[54:55], 0.5, v[98:99] op_sel_hi:[1,0,1]
	v_pk_fma_f32 v[54:55], v[52:53], 0.5, v[66:67] op_sel_hi:[1,0,1]
	v_mul_f32_e32 v52, v57, v57
	v_mul_f32_e32 v53, v59, v59
	v_fmac_f32_e32 v52, v56, v56
	v_fmac_f32_e32 v53, v58, v58
	v_add_f32_e32 v52, v52, v53
	v_mul_f32_e32 v53, v55, v55
	v_fmac_f32_e32 v53, v54, v54
	v_add_f32_e32 v52, v53, v52
	v_mul_f32_e32 v53, v63, v63
	v_fmac_f32_e32 v53, v62, v62
	v_add_f32_e32 v52, v53, v52
	v_add_f32_e32 v64, v100, v52
	v_cvt_pk_bf16_f32 v52, v56, v57
	v_cvt_pk_bf16_f32 v53, v58, v59
	v_cvt_pk_bf16_f32 v54, v54, v55
	v_cvt_pk_bf16_f32 v55, v62, v63
	global_store_dwordx4 v[60:61], v[52:55], off offset:256
	ds_bpermute_b32 v52, v195, v64
	s_waitcnt lgkmcnt(0)
	v_add_f32_e32 v52, v64, v52
	ds_bpermute_b32 v53, v180, v52
	s_and_saveexec_b64 s[44:45], s[8:9]
	s_cbranch_execz .LBB0_637
	s_waitcnt lgkmcnt(0)
	v_add_f32_e32 v52, v52, v53
	ds_write_b32 v193, v52 offset:2048

.LBB0_671:
	s_lshl_b32 s17, s17, 8
	v_add_u32_e32 v202, s17, v3
	v_lshl_or_b32 v200, s16, 8, v227
	v_readlane_b32 s68, v251, 22
	v_ashrrev_i32_e32 v201, 31, v200
	v_readlane_b32 s69, v251, 23
	v_ashrrev_i32_e32 v203, 31, v202
	v_lshlrev_b64 v[132:133], 12, v[202:203]
	v_lshl_add_u64 v[204:205], v[200:201], 2, s[68:69]
	v_lshl_add_u64 v[132:133], v[204:205], 0, v[132:133]
	global_load_dwordx4 v[218:221], v[132:133], off nt
	global_load_dwordx4 v[232:235], v[132:133], off offset:16 nt
	global_load_dwordx4 v[236:239], v[132:133], off offset:512 nt
	global_load_dwordx4 v[240:243], v[132:133], off offset:528 nt
	v_or_b32_e32 v210, 16, v202
	v_or_b32_e32 v208, 32, v202
	v_or_b32_e32 v206, 48, v202
	v_ashrrev_i32_e32 v211, 31, v210
	v_ashrrev_i32_e32 v209, 31, v208
	v_ashrrev_i32_e32 v207, 31, v206
	v_lshlrev_b64 v[132:133], 12, v[210:211]
	v_lshlrev_b64 v[134:135], 12, v[208:209]
	v_lshlrev_b64 v[136:137], 12, v[206:207]
	v_lshl_add_u64 v[132:133], v[204:205], 0, v[132:133]
	v_lshl_add_u64 v[134:135], v[204:205], 0, v[134:135]
	v_lshl_add_u64 v[136:137], v[204:205], 0, v[136:137]
	global_load_dwordx4 v[172:175], v[132:133], off offset:16 nt
	global_load_dwordx4 v[176:179], v[132:133], off nt
	global_load_dwordx4 v[164:167], v[132:133], off offset:528 nt
	global_load_dwordx4 v[168:171], v[132:133], off offset:512 nt
	global_load_dwordx4 v[156:159], v[134:135], off offset:16 nt
	global_load_dwordx4 v[160:163], v[134:135], off nt
	global_load_dwordx4 v[148:151], v[134:135], off offset:528 nt
	global_load_dwordx4 v[152:155], v[134:135], off offset:512 nt
	global_load_dwordx4 v[140:143], v[136:137], off offset:16 nt
	global_load_dwordx4 v[144:147], v[136:137], off nt
	s_nop 0
	global_load_dwordx4 v[132:135], v[136:137], off offset:528 nt
	s_nop 0
	global_load_dwordx4 v[136:139], v[136:137], off offset:512 nt
	v_and_b32_e32 v182, 64, v216
	v_xor_b32_e32 v180, 16, v216
	v_add_u32_e32 v182, 64, v182
	v_xor_b32_e32 v183, 32, v216
	v_cmp_lt_i32_e32 vcc, v180, v182
	v_readlane_b32 s70, v251, 24
	v_readlane_b32 s71, v251, 25
	v_cndmask_b32_e32 v180, v216, v180, vcc
	v_cmp_lt_i32_e32 vcc, v183, v182
	v_lshlrev_b32_e32 v230, 2, v180
	v_readlane_b32 s72, v251, 26
	v_cndmask_b32_e32 v182, v216, v183, vcc
	v_lshlrev_b32_e32 v180, 2, v182
	v_lshlrev_b64 v[182:183], 11, v[202:203]
	v_readlane_b32 s73, v251, 27
	v_readlane_b32 s74, v251, 28
	v_readlane_b32 s75, v251, 29
	v_readlane_b32 s76, v251, 30
	v_readlane_b32 s77, v251, 31
	v_readlane_b32 s78, v251, 32
	v_readlane_b32 s79, v251, 33
	v_readlane_b32 s80, v251, 34
	v_readlane_b32 s81, v251, 35
	v_readlane_b32 s82, v251, 36
	v_readlane_b32 s83, v251, 37
	s_waitcnt vmcnt(0)
	v_pk_fma_f32 v[130:131], v[130:131], 0.5, v[220:221] op_sel_hi:[1,0,1]
	v_pk_fma_f32 v[128:129], v[128:129], 0.5, v[218:219] op_sel_hi:[1,0,1]
	v_pk_fma_f32 v[126:127], v[126:127], 0.5, v[234:235] op_sel_hi:[1,0,1]
	v_pk_fma_f32 v[124:125], v[124:125], 0.5, v[232:233] op_sel_hi:[1,0,1]
	v_pk_fma_f32 v[122:123], v[122:123], 0.5, v[238:239] op_sel_hi:[1,0,1]
	v_pk_fma_f32 v[120:121], v[120:121], 0.5, v[236:237] op_sel_hi:[1,0,1]
	v_pk_fma_f32 v[184:185], v[118:119], 0.5, v[242:243] op_sel_hi:[1,0,1]
	v_pk_fma_f32 v[218:219], v[116:117], 0.5, v[240:241] op_sel_hi:[1,0,1]
	v_mul_f32_e32 v203, v129, v129
	v_mul_f32_e32 v220, v131, v131
	v_mul_f32_e32 v221, v125, v125
	v_mul_f32_e32 v224, v127, v127
	v_cvt_pk_bf16_f32 v118, v124, v125
	v_cvt_pk_bf16_f32 v119, v126, v127
	v_mul_f32_e32 v125, v121, v121
	v_mul_f32_e32 v127, v123, v123
	v_cvt_pk_bf16_f32 v116, v128, v129
	v_mul_f32_e32 v129, v219, v219
	v_fmac_f32_e32 v203, v128, v128
	v_fmac_f32_e32 v220, v130, v130
	v_fmac_f32_e32 v125, v120, v120
	v_fmac_f32_e32 v127, v122, v122
	v_cvt_pk_bf16_f32 v117, v130, v131
	v_mul_f32_e32 v131, v185, v185
	v_fmac_f32_e32 v221, v124, v124
	v_fmac_f32_e32 v129, v218, v218
	v_add_f32_e32 v124, v203, v220
	v_add_f32_e32 v125, v125, v127
	v_fmac_f32_e32 v224, v126, v126
	v_fmac_f32_e32 v131, v184, v184
	v_add_f32_e32 v124, v221, v124
	v_add_f32_e32 v125, v129, v125
	v_add_f32_e32 v124, v224, v124
	v_add_f32_e32 v125, v131, v125
	v_add_f32_e32 v126, v124, v125
	ds_bpermute_b32 v127, v230, v126
	v_lshl_add_u64 v[124:125], s[42:43], 0, v[182:183]
	v_lshl_add_u64 v[124:125], v[200:201], 1, v[124:125]
	global_store_dwordx4 v[124:125], v[116:119], off
	s_waitcnt lgkmcnt(0)
	s_nop 0
	v_add_f32_e32 v116, v126, v127
	ds_bpermute_b32 v117, v180, v116
	v_cvt_pk_bf16_f32 v118, v120, v121
	v_cvt_pk_bf16_f32 v119, v122, v123
	v_cvt_pk_bf16_f32 v120, v218, v219
	v_cvt_pk_bf16_f32 v121, v184, v185
	global_store_dwordx4 v[124:125], v[118:121], off offset:256
	s_and_saveexec_b64 s[26:27], s[6:7]
	s_cbranch_execz .LBB0_673
	s_waitcnt lgkmcnt(0)
	v_add_f32_e32 v116, v116, v117
	ds_write_b32 v228, v116

.LBB0_679:
	s_or_b64 exec, exec, s[26:27]
	v_add_u32_e32 v138, 0x80, v202
	v_ashrrev_i32_e32 v139, 31, v138
	s_waitcnt lgkmcnt(0)
	v_lshlrev_b64 v[68:69], 12, v[138:139]
	v_lshl_add_u64 v[68:69], v[204:205], 0, v[68:69]
	global_load_dwordx4 v[122:125], v[68:69], off nt
	global_load_dwordx4 v[126:129], v[68:69], off offset:16 nt
	global_load_dwordx4 v[130:133], v[68:69], off offset:512 nt
	global_load_dwordx4 v[134:137], v[68:69], off offset:528 nt
	v_add_u32_e32 v120, 0x90, v202
	v_add_u32_e32 v118, 0xa0, v202
	v_add_u32_e32 v116, 0xb0, v202
	v_ashrrev_i32_e32 v121, 31, v120
	v_ashrrev_i32_e32 v119, 31, v118
	v_ashrrev_i32_e32 v117, 31, v116
	v_lshlrev_b64 v[68:69], 12, v[120:121]
	v_lshlrev_b64 v[70:71], 12, v[118:119]
	v_lshlrev_b64 v[72:73], 12, v[116:117]
	v_lshl_add_u64 v[68:69], v[204:205], 0, v[68:69]
	v_lshl_add_u64 v[70:71], v[204:205], 0, v[70:71]
	v_lshl_add_u64 v[72:73], v[204:205], 0, v[72:73]
	global_load_dwordx4 v[108:111], v[68:69], off offset:16 nt
	global_load_dwordx4 v[112:115], v[68:69], off nt
	global_load_dwordx4 v[100:103], v[68:69], off offset:528 nt
	global_load_dwordx4 v[104:107], v[68:69], off offset:512 nt
	global_load_dwordx4 v[92:95], v[70:71], off offset:16 nt
	global_load_dwordx4 v[96:99], v[70:71], off nt
	global_load_dwordx4 v[84:87], v[70:71], off offset:528 nt
	global_load_dwordx4 v[88:91], v[70:71], off offset:512 nt
	global_load_dwordx4 v[76:79], v[72:73], off offset:16 nt
	global_load_dwordx4 v[80:83], v[72:73], off nt
	s_nop 0
	global_load_dwordx4 v[68:71], v[72:73], off offset:528 nt
	s_nop 0
	global_load_dwordx4 v[72:75], v[72:73], off offset:512 nt
	v_lshlrev_b64 v[138:139], 11, v[138:139]
	s_waitcnt vmcnt(15)
	v_pk_fma_f32 v[66:67], v[66:67], 0.5, v[124:125] op_sel_hi:[1,0,1]
	v_pk_fma_f32 v[64:65], v[64:65], 0.5, v[122:123] op_sel_hi:[1,0,1]
	s_waitcnt vmcnt(14)
	v_pk_fma_f32 v[62:63], v[62:63], 0.5, v[128:129] op_sel_hi:[1,0,1]
	v_pk_fma_f32 v[60:61], v[60:61], 0.5, v[126:127] op_sel_hi:[1,0,1]
	s_waitcnt vmcnt(13)
	v_pk_fma_f32 v[58:59], v[58:59], 0.5, v[132:133] op_sel_hi:[1,0,1]
	v_pk_fma_f32 v[56:57], v[56:57], 0.5, v[130:131] op_sel_hi:[1,0,1]
	s_waitcnt vmcnt(12)
	v_pk_fma_f32 v[122:123], v[54:55], 0.5, v[136:137] op_sel_hi:[1,0,1]
	v_pk_fma_f32 v[124:125], v[52:53], 0.5, v[134:135] op_sel_hi:[1,0,1]
	v_mul_f32_e32 v126, v65, v65
	v_mul_f32_e32 v127, v67, v67
	v_mul_f32_e32 v128, v61, v61
	v_mul_f32_e32 v129, v63, v63
	v_cvt_pk_bf16_f32 v54, v60, v61
	v_cvt_pk_bf16_f32 v55, v62, v63
	v_mul_f32_e32 v61, v57, v57
	v_mul_f32_e32 v63, v59, v59
	v_cvt_pk_bf16_f32 v52, v64, v65
	v_mul_f32_e32 v65, v125, v125
	v_fmac_f32_e32 v126, v64, v64
	v_fmac_f32_e32 v127, v66, v66
	v_fmac_f32_e32 v61, v56, v56
	v_fmac_f32_e32 v63, v58, v58
	v_cvt_pk_bf16_f32 v53, v66, v67
	v_mul_f32_e32 v67, v123, v123
	v_fmac_f32_e32 v128, v60, v60
	v_fmac_f32_e32 v65, v124, v124
	v_add_f32_e32 v60, v126, v127
	v_add_f32_e32 v61, v61, v63
	v_fmac_f32_e32 v129, v62, v62
	v_fmac_f32_e32 v67, v122, v122
	v_add_f32_e32 v60, v128, v60
	v_add_f32_e32 v61, v65, v61
	v_add_f32_e32 v60, v129, v60
	v_add_f32_e32 v61, v67, v61
	v_add_f32_e32 v62, v60, v61
	ds_bpermute_b32 v63, v230, v62
	v_lshl_add_u64 v[60:61], s[42:43], 0, v[138:139]
	v_lshl_add_u64 v[60:61], v[200:201], 1, v[60:61]
	global_store_dwordx4 v[60:61], v[52:55], off
	s_waitcnt lgkmcnt(0)
	s_nop 0
	v_add_f32_e32 v52, v62, v63
	ds_bpermute_b32 v53, v180, v52
	v_cvt_pk_bf16_f32 v54, v56, v57
	v_cvt_pk_bf16_f32 v55, v58, v59
	v_cvt_pk_bf16_f32 v56, v124, v125
	v_cvt_pk_bf16_f32 v57, v122, v123
	global_store_dwordx4 v[60:61], v[54:57], off offset:256
	s_and_saveexec_b64 s[26:27], s[6:7]
	s_cbranch_execz .LBB0_681
	s_waitcnt lgkmcnt(0)
	v_add_f32_e32 v52, v52, v53
	ds_write_b32 v228, v52 offset:2048
